# weight-conversion jobs: the 32 row loads of each 64x32 block issued together (one memory round trip per block instead of 32), into dead accumulator registers
# speedup vs baseline: 1.0554x; 1.0554x over previous
; #define LAS __attribute__((address_space(3)))
; DI void cvt_item(const CvtJob& J, int item, LAS float* scr, int lane) {
;     const int nblk = (J.N + 31) >> 5, kb = item / nblk, nb = item % nblk, k0 = 64 * kb, n0 = 32 * nb;
; #pragma unroll 8
;     for (int i = 0; i < 32; ++i) { const int kk = 2 * i + (lane >> 5), k = k0 + kk, n = n0 + (lane & 31);
;         float v = 0.f; if (k < J.K && n < J.N) { v = J.src[(size_t)k * J.ldw + n]; if (J.smode == 1) v *= J.scale[k]; else if (J.smode == 2) v *= (1.f - J.scale[k]); }
;         scr[kk * 33 + (lane & 31)] = v; }
.LBB0_20:
	v_ashrrev_i32_e32 v4, 31, v25
	s_waitcnt vmcnt(0)
	v_xor_b32_e32 v12, s66, v4
	v_sub_u32_e32 v4, 0, v25
	v_max_i32_e32 v4, v25, v4
	v_mul_hi_u32 v6, v4, v26
	v_mul_lo_u32 v7, v6, s63
	v_sub_u32_e32 v4, v4, v7
	v_add_u32_e32 v7, 1, v6
	v_cmp_le_u32_e32 vcc, s63, v4
	s_mov_b32 s26, 0
	v_mov_b32_e32 v15, v22
	v_cndmask_b32_e32 v6, v6, v7, vcc
	v_subrev_u32_e32 v7, s63, v4
	v_cndmask_b32_e32 v4, v4, v7, vcc
	v_add_u32_e32 v7, 1, v6
	v_cmp_le_u32_e32 vcc, s63, v4
	s_nop 1
	v_cndmask_b32_e32 v4, v6, v7, vcc
	v_xor_b32_e32 v13, v4, v12
	v_sub_u32_e32 v6, v13, v12
	v_mul_lo_u32 v4, v6, s62
	v_sub_u32_e32 v4, v25, v4
	v_lshlrev_b32_e32 v27, 5, v4
	v_lshlrev_b32_e32 v6, 6, v6
	v_or_b32_e32 v10, v27, v16
	v_ashrrev_i32_e32 v11, 31, v10
	v_ashrrev_i32_e32 v7, 31, v6
	v_lshl_add_u64 v[8:9], v[10:11], 2, s[4:5]
	v_cmp_gt_i32_e64 s[2:3], s15, v10
	v_or_b32_e32 v10, v0, v6
	v_mov_b32_e32 v11, v7
	v_lshl_or_b32 v13, v13, 6, v0
	v_lshlrev_b32_e32 v12, 6, v12
	v_sub_u32_e32 v14, v13, v12
	v_lshl_add_u64 v[10:11], v[10:11], 2, s[18:19]
	s_mov_b64 s[22:23], exec
	v_sub_u32_e32 v12, s14, v14
	v_add_u32_e32 v12, 1, v12
	v_ashrrev_i32_e32 v12, 1, v12
	v_med3_i32 v12, v12, 0, 32
	v_cndmask_b32_e64 v12, 0, v12, s[2:3]
	v_mad_i64_i32 v[28:29], s[24:25], v14, s64, 0
	v_lshl_add_u64 v[28:29], v[28:29], 2, v[8:9]
	s_lshl_b32 s24, s64, 3
	s_mov_b32 s25, 0
	v_mov_b32_e32 v64, 0
	v_mov_b32_e32 v65, 0
	v_mov_b32_e32 v66, 0
	v_mov_b32_e32 v67, 0
	v_mov_b32_e32 v68, 0
	v_mov_b32_e32 v69, 0
	v_mov_b32_e32 v70, 0
	v_mov_b32_e32 v71, 0
	v_mov_b32_e32 v72, 0
	v_mov_b32_e32 v73, 0
	v_mov_b32_e32 v74, 0
	v_mov_b32_e32 v75, 0
	v_mov_b32_e32 v76, 0
	v_mov_b32_e32 v77, 0
	v_mov_b32_e32 v78, 0
	v_mov_b32_e32 v79, 0
	v_mov_b32_e32 v80, 0
	v_mov_b32_e32 v81, 0
	v_mov_b32_e32 v82, 0
	v_mov_b32_e32 v83, 0
	v_mov_b32_e32 v84, 0
	v_mov_b32_e32 v85, 0
	v_mov_b32_e32 v86, 0
	v_mov_b32_e32 v87, 0
	v_mov_b32_e32 v88, 0
	v_mov_b32_e32 v89, 0
	v_mov_b32_e32 v90, 0
	v_mov_b32_e32 v91, 0
	v_mov_b32_e32 v92, 0
	v_mov_b32_e32 v93, 0
	v_mov_b32_e32 v94, 0
	v_mov_b32_e32 v95, 0
	v_cmpx_lt_i32_e32 vcc, 0, v12
	global_load_dword v64, v[28:29], off
	v_lshl_add_u64 v[28:29], v[28:29], 0, s[24:25]
	v_cmpx_lt_i32_e32 vcc, 1, v12
	global_load_dword v65, v[28:29], off
	v_lshl_add_u64 v[28:29], v[28:29], 0, s[24:25]
	v_cmpx_lt_i32_e32 vcc, 2, v12
	global_load_dword v66, v[28:29], off
	v_lshl_add_u64 v[28:29], v[28:29], 0, s[24:25]
	v_cmpx_lt_i32_e32 vcc, 3, v12
	global_load_dword v67, v[28:29], off
	v_lshl_add_u64 v[28:29], v[28:29], 0, s[24:25]
	v_cmpx_lt_i32_e32 vcc, 4, v12
	global_load_dword v68, v[28:29], off
	v_lshl_add_u64 v[28:29], v[28:29], 0, s[24:25]
	v_cmpx_lt_i32_e32 vcc, 5, v12
	global_load_dword v69, v[28:29], off
	v_lshl_add_u64 v[28:29], v[28:29], 0, s[24:25]
	v_cmpx_lt_i32_e32 vcc, 6, v12
	global_load_dword v70, v[28:29], off
	v_lshl_add_u64 v[28:29], v[28:29], 0, s[24:25]
	v_cmpx_lt_i32_e32 vcc, 7, v12
	global_load_dword v71, v[28:29], off
	v_lshl_add_u64 v[28:29], v[28:29], 0, s[24:25]
	v_cmpx_lt_i32_e32 vcc, 8, v12
	global_load_dword v72, v[28:29], off
	v_lshl_add_u64 v[28:29], v[28:29], 0, s[24:25]
	v_cmpx_lt_i32_e32 vcc, 9, v12
	global_load_dword v73, v[28:29], off
	v_lshl_add_u64 v[28:29], v[28:29], 0, s[24:25]
	v_cmpx_lt_i32_e32 vcc, 10, v12
	global_load_dword v74, v[28:29], off
	v_lshl_add_u64 v[28:29], v[28:29], 0, s[24:25]
	v_cmpx_lt_i32_e32 vcc, 11, v12
	global_load_dword v75, v[28:29], off
	v_lshl_add_u64 v[28:29], v[28:29], 0, s[24:25]
	v_cmpx_lt_i32_e32 vcc, 12, v12
	global_load_dword v76, v[28:29], off
	v_lshl_add_u64 v[28:29], v[28:29], 0, s[24:25]
	v_cmpx_lt_i32_e32 vcc, 13, v12
	global_load_dword v77, v[28:29], off
	v_lshl_add_u64 v[28:29], v[28:29], 0, s[24:25]
	v_cmpx_lt_i32_e32 vcc, 14, v12
	global_load_dword v78, v[28:29], off
	v_lshl_add_u64 v[28:29], v[28:29], 0, s[24:25]
	v_cmpx_lt_i32_e32 vcc, 15, v12
	global_load_dword v79, v[28:29], off
	v_lshl_add_u64 v[28:29], v[28:29], 0, s[24:25]
	v_cmpx_lt_i32_e32 vcc, 16, v12
	global_load_dword v80, v[28:29], off
	v_lshl_add_u64 v[28:29], v[28:29], 0, s[24:25]
	v_cmpx_lt_i32_e32 vcc, 17, v12
	global_load_dword v81, v[28:29], off
	v_lshl_add_u64 v[28:29], v[28:29], 0, s[24:25]
	v_cmpx_lt_i32_e32 vcc, 18, v12
	global_load_dword v82, v[28:29], off
	v_lshl_add_u64 v[28:29], v[28:29], 0, s[24:25]
	v_cmpx_lt_i32_e32 vcc, 19, v12
	global_load_dword v83, v[28:29], off
	v_lshl_add_u64 v[28:29], v[28:29], 0, s[24:25]
	v_cmpx_lt_i32_e32 vcc, 20, v12
	global_load_dword v84, v[28:29], off
	v_lshl_add_u64 v[28:29], v[28:29], 0, s[24:25]
	v_cmpx_lt_i32_e32 vcc, 21, v12
	global_load_dword v85, v[28:29], off
	v_lshl_add_u64 v[28:29], v[28:29], 0, s[24:25]
	v_cmpx_lt_i32_e32 vcc, 22, v12
	global_load_dword v86, v[28:29], off
	v_lshl_add_u64 v[28:29], v[28:29], 0, s[24:25]
	v_cmpx_lt_i32_e32 vcc, 23, v12
	global_load_dword v87, v[28:29], off
	v_lshl_add_u64 v[28:29], v[28:29], 0, s[24:25]
	v_cmpx_lt_i32_e32 vcc, 24, v12
	global_load_dword v88, v[28:29], off
	v_lshl_add_u64 v[28:29], v[28:29], 0, s[24:25]
	v_cmpx_lt_i32_e32 vcc, 25, v12
	global_load_dword v89, v[28:29], off
	v_lshl_add_u64 v[28:29], v[28:29], 0, s[24:25]
	v_cmpx_lt_i32_e32 vcc, 26, v12
	global_load_dword v90, v[28:29], off
	v_lshl_add_u64 v[28:29], v[28:29], 0, s[24:25]
	v_cmpx_lt_i32_e32 vcc, 27, v12
	global_load_dword v91, v[28:29], off
	v_lshl_add_u64 v[28:29], v[28:29], 0, s[24:25]
	v_cmpx_lt_i32_e32 vcc, 28, v12
	global_load_dword v92, v[28:29], off
	v_lshl_add_u64 v[28:29], v[28:29], 0, s[24:25]
	v_cmpx_lt_i32_e32 vcc, 29, v12
	global_load_dword v93, v[28:29], off
	v_lshl_add_u64 v[28:29], v[28:29], 0, s[24:25]
	v_cmpx_lt_i32_e32 vcc, 30, v12
	global_load_dword v94, v[28:29], off
	v_lshl_add_u64 v[28:29], v[28:29], 0, s[24:25]
	v_cmpx_lt_i32_e32 vcc, 31, v12
	global_load_dword v95, v[28:29], off
	s_mov_b64 exec, s[22:23]
	s_cmp_eq_u32 s65, 0
	s_cbranch_scc1 .Lcvt0_plain
; DI void cvt_item(const CvtJob& J, int item, LAS float* scr, int lane) {
;     ...
;         float v = 0.f; if (k < J.K && n < J.N) { v = J.src[(size_t)k * J.ldw + n]; if (J.smode == 1) v *= J.scale[k]; else if (J.smode == 2) v *= (1.f - J.scale[k]); }
	v_lshlrev_b32_e32 v13, 2, v14
	v_cmpx_lt_i32_e32 vcc, 0, v12
	global_load_dword v96, v13, s[6:7]
	v_cmpx_lt_i32_e32 vcc, 1, v12
	global_load_dword v97, v13, s[6:7] offset:8
	v_cmpx_lt_i32_e32 vcc, 2, v12
	global_load_dword v98, v13, s[6:7] offset:16
	v_cmpx_lt_i32_e32 vcc, 3, v12
	global_load_dword v99, v13, s[6:7] offset:24
	v_cmpx_lt_i32_e32 vcc, 4, v12
	global_load_dword v100, v13, s[6:7] offset:32
	v_cmpx_lt_i32_e32 vcc, 5, v12
	global_load_dword v101, v13, s[6:7] offset:40
	v_cmpx_lt_i32_e32 vcc, 6, v12
	global_load_dword v102, v13, s[6:7] offset:48
	v_cmpx_lt_i32_e32 vcc, 7, v12
	global_load_dword v103, v13, s[6:7] offset:56
	v_cmpx_lt_i32_e32 vcc, 8, v12
	global_load_dword v104, v13, s[6:7] offset:64
	v_cmpx_lt_i32_e32 vcc, 9, v12
	global_load_dword v105, v13, s[6:7] offset:72
	v_cmpx_lt_i32_e32 vcc, 10, v12
	global_load_dword v106, v13, s[6:7] offset:80
	v_cmpx_lt_i32_e32 vcc, 11, v12
	global_load_dword v107, v13, s[6:7] offset:88
	v_cmpx_lt_i32_e32 vcc, 12, v12
	global_load_dword v108, v13, s[6:7] offset:96
	v_cmpx_lt_i32_e32 vcc, 13, v12
	global_load_dword v109, v13, s[6:7] offset:104
	v_cmpx_lt_i32_e32 vcc, 14, v12
	global_load_dword v110, v13, s[6:7] offset:112
	v_cmpx_lt_i32_e32 vcc, 15, v12
	global_load_dword v111, v13, s[6:7] offset:120
	v_cmpx_lt_i32_e32 vcc, 16, v12
	global_load_dword v112, v13, s[6:7] offset:128
	v_cmpx_lt_i32_e32 vcc, 17, v12
	global_load_dword v113, v13, s[6:7] offset:136
	v_cmpx_lt_i32_e32 vcc, 18, v12
	global_load_dword v114, v13, s[6:7] offset:144
	v_cmpx_lt_i32_e32 vcc, 19, v12
	global_load_dword v115, v13, s[6:7] offset:152
	v_cmpx_lt_i32_e32 vcc, 20, v12
	global_load_dword v116, v13, s[6:7] offset:160
	v_cmpx_lt_i32_e32 vcc, 21, v12
	global_load_dword v117, v13, s[6:7] offset:168
	v_cmpx_lt_i32_e32 vcc, 22, v12
	global_load_dword v118, v13, s[6:7] offset:176
	v_cmpx_lt_i32_e32 vcc, 23, v12
	global_load_dword v119, v13, s[6:7] offset:184
	v_cmpx_lt_i32_e32 vcc, 24, v12
	global_load_dword v120, v13, s[6:7] offset:192
	v_cmpx_lt_i32_e32 vcc, 25, v12
	global_load_dword v121, v13, s[6:7] offset:200
	v_cmpx_lt_i32_e32 vcc, 26, v12
	global_load_dword v122, v13, s[6:7] offset:208
	v_cmpx_lt_i32_e32 vcc, 27, v12
	global_load_dword v123, v13, s[6:7] offset:216
	v_cmpx_lt_i32_e32 vcc, 28, v12
	global_load_dword v124, v13, s[6:7] offset:224
	v_cmpx_lt_i32_e32 vcc, 29, v12
	global_load_dword v125, v13, s[6:7] offset:232
	v_cmpx_lt_i32_e32 vcc, 30, v12
	global_load_dword v126, v13, s[6:7] offset:240
	v_cmpx_lt_i32_e32 vcc, 31, v12
	global_load_dword v127, v13, s[6:7] offset:248
	s_waitcnt vmcnt(0)
	s_mov_b64 exec, s[22:23]
	s_cmp_eq_u32 s65, 2
	s_cbranch_scc1 .Lcvt0_one_minus
	v_cmpx_lt_i32_e32 vcc, 0, v12
	v_mul_f32_e32 v64, v64, v96
	v_cmpx_lt_i32_e32 vcc, 1, v12
	v_mul_f32_e32 v65, v65, v97
	v_cmpx_lt_i32_e32 vcc, 2, v12
	v_mul_f32_e32 v66, v66, v98
	v_cmpx_lt_i32_e32 vcc, 3, v12
	v_mul_f32_e32 v67, v67, v99
	v_cmpx_lt_i32_e32 vcc, 4, v12
	v_mul_f32_e32 v68, v68, v100
	v_cmpx_lt_i32_e32 vcc, 5, v12
	v_mul_f32_e32 v69, v69, v101
	v_cmpx_lt_i32_e32 vcc, 6, v12
	v_mul_f32_e32 v70, v70, v102
	v_cmpx_lt_i32_e32 vcc, 7, v12
	v_mul_f32_e32 v71, v71, v103
	v_cmpx_lt_i32_e32 vcc, 8, v12
	v_mul_f32_e32 v72, v72, v104
	v_cmpx_lt_i32_e32 vcc, 9, v12
	v_mul_f32_e32 v73, v73, v105
	v_cmpx_lt_i32_e32 vcc, 10, v12
	v_mul_f32_e32 v74, v74, v106
	v_cmpx_lt_i32_e32 vcc, 11, v12
	v_mul_f32_e32 v75, v75, v107
	v_cmpx_lt_i32_e32 vcc, 12, v12
	v_mul_f32_e32 v76, v76, v108
	v_cmpx_lt_i32_e32 vcc, 13, v12
	v_mul_f32_e32 v77, v77, v109
	v_cmpx_lt_i32_e32 vcc, 14, v12
	v_mul_f32_e32 v78, v78, v110
	v_cmpx_lt_i32_e32 vcc, 15, v12
	v_mul_f32_e32 v79, v79, v111
	v_cmpx_lt_i32_e32 vcc, 16, v12
	v_mul_f32_e32 v80, v80, v112
	v_cmpx_lt_i32_e32 vcc, 17, v12
	v_mul_f32_e32 v81, v81, v113
	v_cmpx_lt_i32_e32 vcc, 18, v12
	v_mul_f32_e32 v82, v82, v114
	v_cmpx_lt_i32_e32 vcc, 19, v12
	v_mul_f32_e32 v83, v83, v115
	v_cmpx_lt_i32_e32 vcc, 20, v12
	v_mul_f32_e32 v84, v84, v116
	v_cmpx_lt_i32_e32 vcc, 21, v12
	v_mul_f32_e32 v85, v85, v117
	v_cmpx_lt_i32_e32 vcc, 22, v12
	v_mul_f32_e32 v86, v86, v118
	v_cmpx_lt_i32_e32 vcc, 23, v12
	v_mul_f32_e32 v87, v87, v119
	v_cmpx_lt_i32_e32 vcc, 24, v12
	v_mul_f32_e32 v88, v88, v120
	v_cmpx_lt_i32_e32 vcc, 25, v12
	v_mul_f32_e32 v89, v89, v121
	v_cmpx_lt_i32_e32 vcc, 26, v12
	v_mul_f32_e32 v90, v90, v122
	v_cmpx_lt_i32_e32 vcc, 27, v12
	v_mul_f32_e32 v91, v91, v123
	v_cmpx_lt_i32_e32 vcc, 28, v12
	v_mul_f32_e32 v92, v92, v124
	v_cmpx_lt_i32_e32 vcc, 29, v12
	v_mul_f32_e32 v93, v93, v125
	v_cmpx_lt_i32_e32 vcc, 30, v12
	v_mul_f32_e32 v94, v94, v126
	v_cmpx_lt_i32_e32 vcc, 31, v12
	v_mul_f32_e32 v95, v95, v127
	s_branch .Lcvt0_plain
; DI void cvt_item(const CvtJob& J, int item, LAS float* scr, int lane) {
;     ...
;         float v = 0.f; if (k < J.K && n < J.N) { v = J.src[(size_t)k * J.ldw + n]; if (J.smode == 1) v *= J.scale[k]; else if (J.smode == 2) v *= (1.f - J.scale[k]); }
;         scr[kk * 33 + (lane & 31)] = v; }
.Lcvt0_one_minus:
	v_cmpx_lt_i32_e32 vcc, 0, v12
	v_sub_f32_e32 v96, 1.0, v96
	v_mul_f32_e32 v64, v64, v96
	v_cmpx_lt_i32_e32 vcc, 1, v12
	v_sub_f32_e32 v97, 1.0, v97
	v_mul_f32_e32 v65, v65, v97
	v_cmpx_lt_i32_e32 vcc, 2, v12
	v_sub_f32_e32 v98, 1.0, v98
	v_mul_f32_e32 v66, v66, v98
	v_cmpx_lt_i32_e32 vcc, 3, v12
	v_sub_f32_e32 v99, 1.0, v99
	v_mul_f32_e32 v67, v67, v99
	v_cmpx_lt_i32_e32 vcc, 4, v12
	v_sub_f32_e32 v100, 1.0, v100
	v_mul_f32_e32 v68, v68, v100
	v_cmpx_lt_i32_e32 vcc, 5, v12
	v_sub_f32_e32 v101, 1.0, v101
	v_mul_f32_e32 v69, v69, v101
	v_cmpx_lt_i32_e32 vcc, 6, v12
	v_sub_f32_e32 v102, 1.0, v102
	v_mul_f32_e32 v70, v70, v102
	v_cmpx_lt_i32_e32 vcc, 7, v12
	v_sub_f32_e32 v103, 1.0, v103
	v_mul_f32_e32 v71, v71, v103
	v_cmpx_lt_i32_e32 vcc, 8, v12
	v_sub_f32_e32 v104, 1.0, v104
	v_mul_f32_e32 v72, v72, v104
	v_cmpx_lt_i32_e32 vcc, 9, v12
	v_sub_f32_e32 v105, 1.0, v105
	v_mul_f32_e32 v73, v73, v105
	v_cmpx_lt_i32_e32 vcc, 10, v12
	v_sub_f32_e32 v106, 1.0, v106
	v_mul_f32_e32 v74, v74, v106
	v_cmpx_lt_i32_e32 vcc, 11, v12
	v_sub_f32_e32 v107, 1.0, v107
	v_mul_f32_e32 v75, v75, v107
	v_cmpx_lt_i32_e32 vcc, 12, v12
	v_sub_f32_e32 v108, 1.0, v108
	v_mul_f32_e32 v76, v76, v108
	v_cmpx_lt_i32_e32 vcc, 13, v12
	v_sub_f32_e32 v109, 1.0, v109
	v_mul_f32_e32 v77, v77, v109
	v_cmpx_lt_i32_e32 vcc, 14, v12
	v_sub_f32_e32 v110, 1.0, v110
	v_mul_f32_e32 v78, v78, v110
	v_cmpx_lt_i32_e32 vcc, 15, v12
	v_sub_f32_e32 v111, 1.0, v111
	v_mul_f32_e32 v79, v79, v111
	v_cmpx_lt_i32_e32 vcc, 16, v12
	v_sub_f32_e32 v112, 1.0, v112
	v_mul_f32_e32 v80, v80, v112
	v_cmpx_lt_i32_e32 vcc, 17, v12
	v_sub_f32_e32 v113, 1.0, v113
	v_mul_f32_e32 v81, v81, v113
	v_cmpx_lt_i32_e32 vcc, 18, v12
	v_sub_f32_e32 v114, 1.0, v114
	v_mul_f32_e32 v82, v82, v114
	v_cmpx_lt_i32_e32 vcc, 19, v12
	v_sub_f32_e32 v115, 1.0, v115
	v_mul_f32_e32 v83, v83, v115
	v_cmpx_lt_i32_e32 vcc, 20, v12
	v_sub_f32_e32 v116, 1.0, v116
	v_mul_f32_e32 v84, v84, v116
	v_cmpx_lt_i32_e32 vcc, 21, v12
	v_sub_f32_e32 v117, 1.0, v117
	v_mul_f32_e32 v85, v85, v117
	v_cmpx_lt_i32_e32 vcc, 22, v12
	v_sub_f32_e32 v118, 1.0, v118
	v_mul_f32_e32 v86, v86, v118
	v_cmpx_lt_i32_e32 vcc, 23, v12
	v_sub_f32_e32 v119, 1.0, v119
	v_mul_f32_e32 v87, v87, v119
	v_cmpx_lt_i32_e32 vcc, 24, v12
	v_sub_f32_e32 v120, 1.0, v120
	v_mul_f32_e32 v88, v88, v120
	v_cmpx_lt_i32_e32 vcc, 25, v12
	v_sub_f32_e32 v121, 1.0, v121
	v_mul_f32_e32 v89, v89, v121
	v_cmpx_lt_i32_e32 vcc, 26, v12
	v_sub_f32_e32 v122, 1.0, v122
	v_mul_f32_e32 v90, v90, v122
	v_cmpx_lt_i32_e32 vcc, 27, v12
	v_sub_f32_e32 v123, 1.0, v123
	v_mul_f32_e32 v91, v91, v123
	v_cmpx_lt_i32_e32 vcc, 28, v12
	v_sub_f32_e32 v124, 1.0, v124
	v_mul_f32_e32 v92, v92, v124
	v_cmpx_lt_i32_e32 vcc, 29, v12
	v_sub_f32_e32 v125, 1.0, v125
	v_mul_f32_e32 v93, v93, v125
	v_cmpx_lt_i32_e32 vcc, 30, v12
	v_sub_f32_e32 v126, 1.0, v126
	v_mul_f32_e32 v94, v94, v126
	v_cmpx_lt_i32_e32 vcc, 31, v12
	v_sub_f32_e32 v127, 1.0, v127
	v_mul_f32_e32 v95, v95, v127
.Lcvt0_plain:
	s_waitcnt vmcnt(0)
	s_mov_b64 exec, s[22:23]
	ds_write_b32 v15, v64
	ds_write_b32 v15, v65 offset:264
	ds_write_b32 v15, v66 offset:528
	ds_write_b32 v15, v67 offset:792
	ds_write_b32 v15, v68 offset:1056
	ds_write_b32 v15, v69 offset:1320
	ds_write_b32 v15, v70 offset:1584
	ds_write_b32 v15, v71 offset:1848
	ds_write_b32 v15, v72 offset:2112
	ds_write_b32 v15, v73 offset:2376
	ds_write_b32 v15, v74 offset:2640
	ds_write_b32 v15, v75 offset:2904
	ds_write_b32 v15, v76 offset:3168
	ds_write_b32 v15, v77 offset:3432
	ds_write_b32 v15, v78 offset:3696
	ds_write_b32 v15, v79 offset:3960
	ds_write_b32 v15, v80 offset:4224
	ds_write_b32 v15, v81 offset:4488
	ds_write_b32 v15, v82 offset:4752
	ds_write_b32 v15, v83 offset:5016
	ds_write_b32 v15, v84 offset:5280
	ds_write_b32 v15, v85 offset:5544
	ds_write_b32 v15, v86 offset:5808
	ds_write_b32 v15, v87 offset:6072
	ds_write_b32 v15, v88 offset:6336
	ds_write_b32 v15, v89 offset:6600
	ds_write_b32 v15, v90 offset:6864
	ds_write_b32 v15, v91 offset:7128
	ds_write_b32 v15, v92 offset:7392
	ds_write_b32 v15, v93 offset:7656
	ds_write_b32 v15, v94 offset:7920
	ds_write_b32 v15, v95 offset:8184
	v_add_u32_e32 v15, 0x2100, v15
	s_movk_i32 s26, 64

; #define LAS __attribute__((address_space(3)))
; DI void cvt_item(const CvtJob& J, int item, LAS float* scr, int lane) {
;     const int nblk = (J.N + 31) >> 5, kb = item / nblk, nb = item % nblk, k0 = 64 * kb, n0 = 32 * nb;
; #pragma unroll 8
;     for (int i = 0; i < 32; ++i) { const int kk = 2 * i + (lane >> 5), k = k0 + kk, n = n0 + (lane & 31);
;         float v = 0.f; if (k < J.K && n < J.N) { v = J.src[(size_t)k * J.ldw + n]; if (J.smode == 1) v *= J.scale[k]; else if (J.smode == 2) v *= (1.f - J.scale[k]); }
;         scr[kk * 33 + (lane & 31)] = v; }
.LBB0_529:
	v_ashrrev_i32_e32 v4, 31, v24
	s_waitcnt vmcnt(0)
	v_xor_b32_e32 v12, s67, v4
	v_sub_u32_e32 v4, 0, v24
	v_max_i32_e32 v4, v24, v4
	v_mul_hi_u32 v6, v4, v25
	v_mul_lo_u32 v7, v6, s64
	v_sub_u32_e32 v4, v4, v7
	v_add_u32_e32 v7, 1, v6
	v_cmp_le_u32_e32 vcc, s64, v4
	s_mov_b32 s22, 0
	v_mov_b32_e32 v15, v21
	v_cndmask_b32_e32 v6, v6, v7, vcc
	v_subrev_u32_e32 v7, s64, v4
	v_cndmask_b32_e32 v4, v4, v7, vcc
	v_add_u32_e32 v7, 1, v6
	v_cmp_le_u32_e32 vcc, s64, v4
	s_nop 1
	v_cndmask_b32_e32 v4, v6, v7, vcc
	v_xor_b32_e32 v13, v4, v12
	v_sub_u32_e32 v6, v13, v12
	v_mul_lo_u32 v4, v6, s63
	v_sub_u32_e32 v4, v24, v4
	v_lshlrev_b32_e32 v26, 5, v4
	v_lshlrev_b32_e32 v6, 6, v6
	v_or_b32_e32 v10, v26, v3
	v_ashrrev_i32_e32 v11, 31, v10
	v_ashrrev_i32_e32 v7, 31, v6
	v_lshl_add_u64 v[8:9], v[10:11], 2, s[4:5]
	v_cmp_gt_i32_e64 s[2:3], s11, v10
	v_or_b32_e32 v10, v0, v6
	v_mov_b32_e32 v11, v7
	v_lshl_or_b32 v13, v13, 6, v0
	v_lshlrev_b32_e32 v12, 6, v12
	v_sub_u32_e32 v14, v13, v12
	v_lshl_add_u64 v[10:11], v[10:11], 2, s[14:15]
	s_mov_b64 s[18:19], exec
	v_sub_u32_e32 v12, s10, v14
	v_add_u32_e32 v12, 1, v12
	v_ashrrev_i32_e32 v12, 1, v12
	v_med3_i32 v12, v12, 0, 32
	v_cndmask_b32_e64 v12, 0, v12, s[2:3]
	v_mad_i64_i32 v[28:29], s[20:21], v14, s65, 0
	v_lshl_add_u64 v[28:29], v[28:29], 2, v[8:9]
	s_lshl_b32 s20, s65, 3
	s_mov_b32 s21, 0
	v_mov_b32_e32 v64, 0
	v_mov_b32_e32 v65, 0
	v_mov_b32_e32 v66, 0
	v_mov_b32_e32 v67, 0
	v_mov_b32_e32 v68, 0
	v_mov_b32_e32 v69, 0
	v_mov_b32_e32 v70, 0
	v_mov_b32_e32 v71, 0
	v_mov_b32_e32 v72, 0
	v_mov_b32_e32 v73, 0
	v_mov_b32_e32 v74, 0
	v_mov_b32_e32 v75, 0
	v_mov_b32_e32 v76, 0
	v_mov_b32_e32 v77, 0
	v_mov_b32_e32 v78, 0
	v_mov_b32_e32 v79, 0
	v_mov_b32_e32 v80, 0
	v_mov_b32_e32 v81, 0
	v_mov_b32_e32 v82, 0
	v_mov_b32_e32 v83, 0
	v_mov_b32_e32 v84, 0
	v_mov_b32_e32 v85, 0
	v_mov_b32_e32 v86, 0
	v_mov_b32_e32 v87, 0
	v_mov_b32_e32 v88, 0
	v_mov_b32_e32 v89, 0
	v_mov_b32_e32 v90, 0
	v_mov_b32_e32 v91, 0
	v_mov_b32_e32 v92, 0
	v_mov_b32_e32 v93, 0
	v_mov_b32_e32 v94, 0
	v_mov_b32_e32 v95, 0
	v_cmpx_lt_i32_e32 vcc, 0, v12
	global_load_dword v64, v[28:29], off
	v_lshl_add_u64 v[28:29], v[28:29], 0, s[20:21]
	v_cmpx_lt_i32_e32 vcc, 1, v12
	global_load_dword v65, v[28:29], off
	v_lshl_add_u64 v[28:29], v[28:29], 0, s[20:21]
	v_cmpx_lt_i32_e32 vcc, 2, v12
	global_load_dword v66, v[28:29], off
	v_lshl_add_u64 v[28:29], v[28:29], 0, s[20:21]
	v_cmpx_lt_i32_e32 vcc, 3, v12
	global_load_dword v67, v[28:29], off
	v_lshl_add_u64 v[28:29], v[28:29], 0, s[20:21]
	v_cmpx_lt_i32_e32 vcc, 4, v12
	global_load_dword v68, v[28:29], off
	v_lshl_add_u64 v[28:29], v[28:29], 0, s[20:21]
	v_cmpx_lt_i32_e32 vcc, 5, v12
	global_load_dword v69, v[28:29], off
	v_lshl_add_u64 v[28:29], v[28:29], 0, s[20:21]
	v_cmpx_lt_i32_e32 vcc, 6, v12
	global_load_dword v70, v[28:29], off
	v_lshl_add_u64 v[28:29], v[28:29], 0, s[20:21]
	v_cmpx_lt_i32_e32 vcc, 7, v12
	global_load_dword v71, v[28:29], off
	v_lshl_add_u64 v[28:29], v[28:29], 0, s[20:21]
	v_cmpx_lt_i32_e32 vcc, 8, v12
	global_load_dword v72, v[28:29], off
	v_lshl_add_u64 v[28:29], v[28:29], 0, s[20:21]
	v_cmpx_lt_i32_e32 vcc, 9, v12
	global_load_dword v73, v[28:29], off
	v_lshl_add_u64 v[28:29], v[28:29], 0, s[20:21]
	v_cmpx_lt_i32_e32 vcc, 10, v12
	global_load_dword v74, v[28:29], off
	v_lshl_add_u64 v[28:29], v[28:29], 0, s[20:21]
	v_cmpx_lt_i32_e32 vcc, 11, v12
	global_load_dword v75, v[28:29], off
	v_lshl_add_u64 v[28:29], v[28:29], 0, s[20:21]
	v_cmpx_lt_i32_e32 vcc, 12, v12
	global_load_dword v76, v[28:29], off
	v_lshl_add_u64 v[28:29], v[28:29], 0, s[20:21]
	v_cmpx_lt_i32_e32 vcc, 13, v12
	global_load_dword v77, v[28:29], off
	v_lshl_add_u64 v[28:29], v[28:29], 0, s[20:21]
	v_cmpx_lt_i32_e32 vcc, 14, v12
	global_load_dword v78, v[28:29], off
	v_lshl_add_u64 v[28:29], v[28:29], 0, s[20:21]
	v_cmpx_lt_i32_e32 vcc, 15, v12
	global_load_dword v79, v[28:29], off
	v_lshl_add_u64 v[28:29], v[28:29], 0, s[20:21]
	v_cmpx_lt_i32_e32 vcc, 16, v12
	global_load_dword v80, v[28:29], off
	v_lshl_add_u64 v[28:29], v[28:29], 0, s[20:21]
	v_cmpx_lt_i32_e32 vcc, 17, v12
	global_load_dword v81, v[28:29], off
	v_lshl_add_u64 v[28:29], v[28:29], 0, s[20:21]
	v_cmpx_lt_i32_e32 vcc, 18, v12
	global_load_dword v82, v[28:29], off
	v_lshl_add_u64 v[28:29], v[28:29], 0, s[20:21]
	v_cmpx_lt_i32_e32 vcc, 19, v12
	global_load_dword v83, v[28:29], off
	v_lshl_add_u64 v[28:29], v[28:29], 0, s[20:21]
	v_cmpx_lt_i32_e32 vcc, 20, v12
	global_load_dword v84, v[28:29], off
	v_lshl_add_u64 v[28:29], v[28:29], 0, s[20:21]
	v_cmpx_lt_i32_e32 vcc, 21, v12
	global_load_dword v85, v[28:29], off
	v_lshl_add_u64 v[28:29], v[28:29], 0, s[20:21]
	v_cmpx_lt_i32_e32 vcc, 22, v12
	global_load_dword v86, v[28:29], off
	v_lshl_add_u64 v[28:29], v[28:29], 0, s[20:21]
	v_cmpx_lt_i32_e32 vcc, 23, v12
	global_load_dword v87, v[28:29], off
	v_lshl_add_u64 v[28:29], v[28:29], 0, s[20:21]
	v_cmpx_lt_i32_e32 vcc, 24, v12
	global_load_dword v88, v[28:29], off
	v_lshl_add_u64 v[28:29], v[28:29], 0, s[20:21]
	v_cmpx_lt_i32_e32 vcc, 25, v12
	global_load_dword v89, v[28:29], off
	v_lshl_add_u64 v[28:29], v[28:29], 0, s[20:21]
	v_cmpx_lt_i32_e32 vcc, 26, v12
	global_load_dword v90, v[28:29], off
	v_lshl_add_u64 v[28:29], v[28:29], 0, s[20:21]
	v_cmpx_lt_i32_e32 vcc, 27, v12
	global_load_dword v91, v[28:29], off
	v_lshl_add_u64 v[28:29], v[28:29], 0, s[20:21]
	v_cmpx_lt_i32_e32 vcc, 28, v12
	global_load_dword v92, v[28:29], off
	v_lshl_add_u64 v[28:29], v[28:29], 0, s[20:21]
	v_cmpx_lt_i32_e32 vcc, 29, v12
	global_load_dword v93, v[28:29], off
	v_lshl_add_u64 v[28:29], v[28:29], 0, s[20:21]
	v_cmpx_lt_i32_e32 vcc, 30, v12
	global_load_dword v94, v[28:29], off
	v_lshl_add_u64 v[28:29], v[28:29], 0, s[20:21]
	v_cmpx_lt_i32_e32 vcc, 31, v12
	global_load_dword v95, v[28:29], off
	s_mov_b64 exec, s[18:19]
	s_cmp_eq_u32 s66, 0
	s_cbranch_scc1 .Lcvt1_plain
; DI void cvt_item(const CvtJob& J, int item, LAS float* scr, int lane) {
;     ...
;         float v = 0.f; if (k < J.K && n < J.N) { v = J.src[(size_t)k * J.ldw + n]; if (J.smode == 1) v *= J.scale[k]; else if (J.smode == 2) v *= (1.f - J.scale[k]); }
	v_lshlrev_b32_e32 v13, 2, v14
	v_cmpx_lt_i32_e32 vcc, 0, v12
	global_load_dword v96, v13, s[6:7]
	v_cmpx_lt_i32_e32 vcc, 1, v12
	global_load_dword v97, v13, s[6:7] offset:8
	v_cmpx_lt_i32_e32 vcc, 2, v12
	global_load_dword v98, v13, s[6:7] offset:16
	v_cmpx_lt_i32_e32 vcc, 3, v12
	global_load_dword v99, v13, s[6:7] offset:24
	v_cmpx_lt_i32_e32 vcc, 4, v12
	global_load_dword v100, v13, s[6:7] offset:32
	v_cmpx_lt_i32_e32 vcc, 5, v12
	global_load_dword v101, v13, s[6:7] offset:40
	v_cmpx_lt_i32_e32 vcc, 6, v12
	global_load_dword v102, v13, s[6:7] offset:48
	v_cmpx_lt_i32_e32 vcc, 7, v12
	global_load_dword v103, v13, s[6:7] offset:56
	v_cmpx_lt_i32_e32 vcc, 8, v12
	global_load_dword v104, v13, s[6:7] offset:64
	v_cmpx_lt_i32_e32 vcc, 9, v12
	global_load_dword v105, v13, s[6:7] offset:72
	v_cmpx_lt_i32_e32 vcc, 10, v12
	global_load_dword v106, v13, s[6:7] offset:80
	v_cmpx_lt_i32_e32 vcc, 11, v12
	global_load_dword v107, v13, s[6:7] offset:88
	v_cmpx_lt_i32_e32 vcc, 12, v12
	global_load_dword v108, v13, s[6:7] offset:96
	v_cmpx_lt_i32_e32 vcc, 13, v12
	global_load_dword v109, v13, s[6:7] offset:104
	v_cmpx_lt_i32_e32 vcc, 14, v12
	global_load_dword v110, v13, s[6:7] offset:112
	v_cmpx_lt_i32_e32 vcc, 15, v12
	global_load_dword v111, v13, s[6:7] offset:120
	v_cmpx_lt_i32_e32 vcc, 16, v12
	global_load_dword v112, v13, s[6:7] offset:128
	v_cmpx_lt_i32_e32 vcc, 17, v12
	global_load_dword v113, v13, s[6:7] offset:136
	v_cmpx_lt_i32_e32 vcc, 18, v12
	global_load_dword v114, v13, s[6:7] offset:144
	v_cmpx_lt_i32_e32 vcc, 19, v12
	global_load_dword v115, v13, s[6:7] offset:152
	v_cmpx_lt_i32_e32 vcc, 20, v12
	global_load_dword v116, v13, s[6:7] offset:160
	v_cmpx_lt_i32_e32 vcc, 21, v12
	global_load_dword v117, v13, s[6:7] offset:168
	v_cmpx_lt_i32_e32 vcc, 22, v12
	global_load_dword v118, v13, s[6:7] offset:176
	v_cmpx_lt_i32_e32 vcc, 23, v12
	global_load_dword v119, v13, s[6:7] offset:184
	v_cmpx_lt_i32_e32 vcc, 24, v12
	global_load_dword v120, v13, s[6:7] offset:192
	v_cmpx_lt_i32_e32 vcc, 25, v12
	global_load_dword v121, v13, s[6:7] offset:200
	v_cmpx_lt_i32_e32 vcc, 26, v12
	global_load_dword v122, v13, s[6:7] offset:208
	v_cmpx_lt_i32_e32 vcc, 27, v12
	global_load_dword v123, v13, s[6:7] offset:216
	v_cmpx_lt_i32_e32 vcc, 28, v12
	global_load_dword v124, v13, s[6:7] offset:224
	v_cmpx_lt_i32_e32 vcc, 29, v12
	global_load_dword v125, v13, s[6:7] offset:232
	v_cmpx_lt_i32_e32 vcc, 30, v12
	global_load_dword v126, v13, s[6:7] offset:240
	v_cmpx_lt_i32_e32 vcc, 31, v12
	global_load_dword v127, v13, s[6:7] offset:248
	s_waitcnt vmcnt(0)
	s_mov_b64 exec, s[18:19]
	s_cmp_eq_u32 s66, 2
	s_cbranch_scc1 .Lcvt1_one_minus
	v_cmpx_lt_i32_e32 vcc, 0, v12
	v_mul_f32_e32 v64, v64, v96
	v_cmpx_lt_i32_e32 vcc, 1, v12
	v_mul_f32_e32 v65, v65, v97
	v_cmpx_lt_i32_e32 vcc, 2, v12
	v_mul_f32_e32 v66, v66, v98
	v_cmpx_lt_i32_e32 vcc, 3, v12
	v_mul_f32_e32 v67, v67, v99
	v_cmpx_lt_i32_e32 vcc, 4, v12
	v_mul_f32_e32 v68, v68, v100
	v_cmpx_lt_i32_e32 vcc, 5, v12
	v_mul_f32_e32 v69, v69, v101
	v_cmpx_lt_i32_e32 vcc, 6, v12
	v_mul_f32_e32 v70, v70, v102
	v_cmpx_lt_i32_e32 vcc, 7, v12
	v_mul_f32_e32 v71, v71, v103
	v_cmpx_lt_i32_e32 vcc, 8, v12
	v_mul_f32_e32 v72, v72, v104
	v_cmpx_lt_i32_e32 vcc, 9, v12
	v_mul_f32_e32 v73, v73, v105
	v_cmpx_lt_i32_e32 vcc, 10, v12
	v_mul_f32_e32 v74, v74, v106
	v_cmpx_lt_i32_e32 vcc, 11, v12
	v_mul_f32_e32 v75, v75, v107
	v_cmpx_lt_i32_e32 vcc, 12, v12
	v_mul_f32_e32 v76, v76, v108
	v_cmpx_lt_i32_e32 vcc, 13, v12
	v_mul_f32_e32 v77, v77, v109
	v_cmpx_lt_i32_e32 vcc, 14, v12
	v_mul_f32_e32 v78, v78, v110
	v_cmpx_lt_i32_e32 vcc, 15, v12
	v_mul_f32_e32 v79, v79, v111
	v_cmpx_lt_i32_e32 vcc, 16, v12
	v_mul_f32_e32 v80, v80, v112
	v_cmpx_lt_i32_e32 vcc, 17, v12
	v_mul_f32_e32 v81, v81, v113
	v_cmpx_lt_i32_e32 vcc, 18, v12
	v_mul_f32_e32 v82, v82, v114
	v_cmpx_lt_i32_e32 vcc, 19, v12
	v_mul_f32_e32 v83, v83, v115
	v_cmpx_lt_i32_e32 vcc, 20, v12
	v_mul_f32_e32 v84, v84, v116
	v_cmpx_lt_i32_e32 vcc, 21, v12
	v_mul_f32_e32 v85, v85, v117
	v_cmpx_lt_i32_e32 vcc, 22, v12
	v_mul_f32_e32 v86, v86, v118
	v_cmpx_lt_i32_e32 vcc, 23, v12
	v_mul_f32_e32 v87, v87, v119
	v_cmpx_lt_i32_e32 vcc, 24, v12
	v_mul_f32_e32 v88, v88, v120
	v_cmpx_lt_i32_e32 vcc, 25, v12
	v_mul_f32_e32 v89, v89, v121
	v_cmpx_lt_i32_e32 vcc, 26, v12
	v_mul_f32_e32 v90, v90, v122
	v_cmpx_lt_i32_e32 vcc, 27, v12
	v_mul_f32_e32 v91, v91, v123
	v_cmpx_lt_i32_e32 vcc, 28, v12
	v_mul_f32_e32 v92, v92, v124
	v_cmpx_lt_i32_e32 vcc, 29, v12
	v_mul_f32_e32 v93, v93, v125
	v_cmpx_lt_i32_e32 vcc, 30, v12
	v_mul_f32_e32 v94, v94, v126
	v_cmpx_lt_i32_e32 vcc, 31, v12
	v_mul_f32_e32 v95, v95, v127
	s_branch .Lcvt1_plain

; DI void cvt_item(const CvtJob& J, int item, LAS float* scr, int lane) {
;     ...
;         scr[kk * 33 + (lane & 31)] = v; }
.Lcvt1_plain:
	s_waitcnt vmcnt(0)
	s_mov_b64 exec, s[18:19]
	ds_write_b32 v15, v64
	ds_write_b32 v15, v65 offset:264
	ds_write_b32 v15, v66 offset:528
	ds_write_b32 v15, v67 offset:792
	ds_write_b32 v15, v68 offset:1056
	ds_write_b32 v15, v69 offset:1320
	ds_write_b32 v15, v70 offset:1584
	ds_write_b32 v15, v71 offset:1848
	ds_write_b32 v15, v72 offset:2112
	ds_write_b32 v15, v73 offset:2376
	ds_write_b32 v15, v74 offset:2640
	ds_write_b32 v15, v75 offset:2904
	ds_write_b32 v15, v76 offset:3168
	ds_write_b32 v15, v77 offset:3432
	ds_write_b32 v15, v78 offset:3696
	ds_write_b32 v15, v79 offset:3960
	ds_write_b32 v15, v80 offset:4224
	ds_write_b32 v15, v81 offset:4488
	ds_write_b32 v15, v82 offset:4752
	ds_write_b32 v15, v83 offset:5016
	ds_write_b32 v15, v84 offset:5280
	ds_write_b32 v15, v85 offset:5544
	ds_write_b32 v15, v86 offset:5808
	ds_write_b32 v15, v87 offset:6072
	ds_write_b32 v15, v88 offset:6336
	ds_write_b32 v15, v89 offset:6600
	ds_write_b32 v15, v90 offset:6864
	ds_write_b32 v15, v91 offset:7128
	ds_write_b32 v15, v92 offset:7392
	ds_write_b32 v15, v93 offset:7656
	ds_write_b32 v15, v94 offset:7920
	ds_write_b32 v15, v95 offset:8184
	v_add_u32_e32 v15, 0x2100, v15
	s_movk_i32 s22, 64

; #define LAS __attribute__((address_space(3)))
; DI void cvt_item(const CvtJob& J, int item, LAS float* scr, int lane) {
;     const int nblk = (J.N + 31) >> 5, kb = item / nblk, nb = item % nblk, k0 = 64 * kb, n0 = 32 * nb;
; #pragma unroll 8
;     for (int i = 0; i < 32; ++i) { const int kk = 2 * i + (lane >> 5), k = k0 + kk, n = n0 + (lane & 31);
;         float v = 0.f; if (k < J.K && n < J.N) { v = J.src[(size_t)k * J.ldw + n]; if (J.smode == 1) v *= J.scale[k]; else if (J.smode == 2) v *= (1.f - J.scale[k]); }
;         scr[kk * 33 + (lane & 31)] = v; }
.LBB0_2041:
	v_ashrrev_i32_e32 v4, 31, v25
	s_waitcnt vmcnt(0)
	v_xor_b32_e32 v12, s75, v4
	v_sub_u32_e32 v4, 0, v25
	v_max_i32_e32 v4, v25, v4
	v_mul_hi_u32 v6, v4, v26
	v_mul_lo_u32 v7, v6, s72
	v_sub_u32_e32 v4, v4, v7
	v_add_u32_e32 v7, 1, v6
	v_cmp_le_u32_e32 vcc, s72, v4
	s_mov_b32 s24, 0
	v_mov_b32_e32 v15, v22
	v_cndmask_b32_e32 v6, v6, v7, vcc
	v_subrev_u32_e32 v7, s72, v4
	v_cndmask_b32_e32 v4, v4, v7, vcc
	v_add_u32_e32 v7, 1, v6
	v_cmp_le_u32_e32 vcc, s72, v4
	s_nop 1
	v_cndmask_b32_e32 v4, v6, v7, vcc
	v_xor_b32_e32 v13, v4, v12
	v_sub_u32_e32 v6, v13, v12
	v_mul_lo_u32 v4, v6, s71
	v_sub_u32_e32 v4, v25, v4
	v_lshlrev_b32_e32 v27, 5, v4
	v_lshlrev_b32_e32 v6, 6, v6
	v_or_b32_e32 v10, v27, v16
	v_ashrrev_i32_e32 v11, 31, v10
	v_ashrrev_i32_e32 v7, 31, v6
	v_lshl_add_u64 v[8:9], v[10:11], 2, s[4:5]
	v_cmp_gt_i32_e64 s[2:3], s13, v10
	v_or_b32_e32 v10, v0, v6
	v_mov_b32_e32 v11, v7
	v_lshl_or_b32 v13, v13, 6, v0
	v_lshlrev_b32_e32 v12, 6, v12
	v_sub_u32_e32 v14, v13, v12
	v_lshl_add_u64 v[10:11], v[10:11], 2, s[16:17]
	s_mov_b64 s[20:21], exec
	v_sub_u32_e32 v12, s12, v14
	v_add_u32_e32 v12, 1, v12
	v_ashrrev_i32_e32 v12, 1, v12
	v_med3_i32 v12, v12, 0, 32
	v_cndmask_b32_e64 v12, 0, v12, s[2:3]
	v_mad_i64_i32 v[28:29], s[22:23], v14, s73, 0
	v_lshl_add_u64 v[28:29], v[28:29], 2, v[8:9]
	s_lshl_b32 s22, s73, 3
	s_mov_b32 s23, 0
	v_mov_b32_e32 v64, 0
	v_mov_b32_e32 v65, 0
	v_mov_b32_e32 v66, 0
	v_mov_b32_e32 v67, 0
	v_mov_b32_e32 v68, 0
	v_mov_b32_e32 v69, 0
	v_mov_b32_e32 v70, 0
	v_mov_b32_e32 v71, 0
	v_mov_b32_e32 v72, 0
	v_mov_b32_e32 v73, 0
	v_mov_b32_e32 v74, 0
	v_mov_b32_e32 v75, 0
	v_mov_b32_e32 v76, 0
	v_mov_b32_e32 v77, 0
	v_mov_b32_e32 v78, 0
	v_mov_b32_e32 v79, 0
	v_mov_b32_e32 v80, 0
	v_mov_b32_e32 v81, 0
	v_mov_b32_e32 v82, 0
	v_mov_b32_e32 v83, 0
	v_mov_b32_e32 v84, 0
	v_mov_b32_e32 v85, 0
	v_mov_b32_e32 v86, 0
	v_mov_b32_e32 v87, 0
	v_mov_b32_e32 v88, 0
	v_mov_b32_e32 v89, 0
	v_mov_b32_e32 v90, 0
	v_mov_b32_e32 v91, 0
	v_mov_b32_e32 v92, 0
	v_mov_b32_e32 v93, 0
	v_mov_b32_e32 v94, 0
	v_mov_b32_e32 v95, 0
	v_cmpx_lt_i32_e32 vcc, 0, v12
	global_load_dword v64, v[28:29], off
	v_lshl_add_u64 v[28:29], v[28:29], 0, s[22:23]
	v_cmpx_lt_i32_e32 vcc, 1, v12
	global_load_dword v65, v[28:29], off
	v_lshl_add_u64 v[28:29], v[28:29], 0, s[22:23]
	v_cmpx_lt_i32_e32 vcc, 2, v12
	global_load_dword v66, v[28:29], off
	v_lshl_add_u64 v[28:29], v[28:29], 0, s[22:23]
	v_cmpx_lt_i32_e32 vcc, 3, v12
	global_load_dword v67, v[28:29], off
	v_lshl_add_u64 v[28:29], v[28:29], 0, s[22:23]
	v_cmpx_lt_i32_e32 vcc, 4, v12
	global_load_dword v68, v[28:29], off
	v_lshl_add_u64 v[28:29], v[28:29], 0, s[22:23]
	v_cmpx_lt_i32_e32 vcc, 5, v12
	global_load_dword v69, v[28:29], off
	v_lshl_add_u64 v[28:29], v[28:29], 0, s[22:23]
	v_cmpx_lt_i32_e32 vcc, 6, v12
	global_load_dword v70, v[28:29], off
	v_lshl_add_u64 v[28:29], v[28:29], 0, s[22:23]
	v_cmpx_lt_i32_e32 vcc, 7, v12
	global_load_dword v71, v[28:29], off
	v_lshl_add_u64 v[28:29], v[28:29], 0, s[22:23]
	v_cmpx_lt_i32_e32 vcc, 8, v12
	global_load_dword v72, v[28:29], off
	v_lshl_add_u64 v[28:29], v[28:29], 0, s[22:23]
	v_cmpx_lt_i32_e32 vcc, 9, v12
	global_load_dword v73, v[28:29], off
	v_lshl_add_u64 v[28:29], v[28:29], 0, s[22:23]
	v_cmpx_lt_i32_e32 vcc, 10, v12
	global_load_dword v74, v[28:29], off
	v_lshl_add_u64 v[28:29], v[28:29], 0, s[22:23]
	v_cmpx_lt_i32_e32 vcc, 11, v12
	global_load_dword v75, v[28:29], off
	v_lshl_add_u64 v[28:29], v[28:29], 0, s[22:23]
	v_cmpx_lt_i32_e32 vcc, 12, v12
	global_load_dword v76, v[28:29], off
	v_lshl_add_u64 v[28:29], v[28:29], 0, s[22:23]
	v_cmpx_lt_i32_e32 vcc, 13, v12
	global_load_dword v77, v[28:29], off
	v_lshl_add_u64 v[28:29], v[28:29], 0, s[22:23]
	v_cmpx_lt_i32_e32 vcc, 14, v12
	global_load_dword v78, v[28:29], off
	v_lshl_add_u64 v[28:29], v[28:29], 0, s[22:23]
	v_cmpx_lt_i32_e32 vcc, 15, v12
	global_load_dword v79, v[28:29], off
	v_lshl_add_u64 v[28:29], v[28:29], 0, s[22:23]
	v_cmpx_lt_i32_e32 vcc, 16, v12
	global_load_dword v80, v[28:29], off
	v_lshl_add_u64 v[28:29], v[28:29], 0, s[22:23]
	v_cmpx_lt_i32_e32 vcc, 17, v12
	global_load_dword v81, v[28:29], off
	v_lshl_add_u64 v[28:29], v[28:29], 0, s[22:23]
	v_cmpx_lt_i32_e32 vcc, 18, v12
	global_load_dword v82, v[28:29], off
	v_lshl_add_u64 v[28:29], v[28:29], 0, s[22:23]
	v_cmpx_lt_i32_e32 vcc, 19, v12
	global_load_dword v83, v[28:29], off
	v_lshl_add_u64 v[28:29], v[28:29], 0, s[22:23]
	v_cmpx_lt_i32_e32 vcc, 20, v12
	global_load_dword v84, v[28:29], off
	v_lshl_add_u64 v[28:29], v[28:29], 0, s[22:23]
	v_cmpx_lt_i32_e32 vcc, 21, v12
	global_load_dword v85, v[28:29], off
	v_lshl_add_u64 v[28:29], v[28:29], 0, s[22:23]
	v_cmpx_lt_i32_e32 vcc, 22, v12
	global_load_dword v86, v[28:29], off
	v_lshl_add_u64 v[28:29], v[28:29], 0, s[22:23]
	v_cmpx_lt_i32_e32 vcc, 23, v12
	global_load_dword v87, v[28:29], off
	v_lshl_add_u64 v[28:29], v[28:29], 0, s[22:23]
	v_cmpx_lt_i32_e32 vcc, 24, v12
	global_load_dword v88, v[28:29], off
	v_lshl_add_u64 v[28:29], v[28:29], 0, s[22:23]
	v_cmpx_lt_i32_e32 vcc, 25, v12
	global_load_dword v89, v[28:29], off
	v_lshl_add_u64 v[28:29], v[28:29], 0, s[22:23]
	v_cmpx_lt_i32_e32 vcc, 26, v12
	global_load_dword v90, v[28:29], off
	v_lshl_add_u64 v[28:29], v[28:29], 0, s[22:23]
	v_cmpx_lt_i32_e32 vcc, 27, v12
	global_load_dword v91, v[28:29], off
	v_lshl_add_u64 v[28:29], v[28:29], 0, s[22:23]
	v_cmpx_lt_i32_e32 vcc, 28, v12
	global_load_dword v92, v[28:29], off
	v_lshl_add_u64 v[28:29], v[28:29], 0, s[22:23]
	v_cmpx_lt_i32_e32 vcc, 29, v12
	global_load_dword v93, v[28:29], off
	v_lshl_add_u64 v[28:29], v[28:29], 0, s[22:23]
	v_cmpx_lt_i32_e32 vcc, 30, v12
	global_load_dword v94, v[28:29], off
	v_lshl_add_u64 v[28:29], v[28:29], 0, s[22:23]
	v_cmpx_lt_i32_e32 vcc, 31, v12
	global_load_dword v95, v[28:29], off
	s_mov_b64 exec, s[20:21]
	s_cmp_eq_u32 s74, 0
	s_cbranch_scc1 .Lcvt2_plain
; DI void cvt_item(const CvtJob& J, int item, LAS float* scr, int lane) {
;     ...
;         float v = 0.f; if (k < J.K && n < J.N) { v = J.src[(size_t)k * J.ldw + n]; if (J.smode == 1) v *= J.scale[k]; else if (J.smode == 2) v *= (1.f - J.scale[k]); }
	v_lshlrev_b32_e32 v13, 2, v14
	v_cmpx_lt_i32_e32 vcc, 0, v12
	global_load_dword v96, v13, s[6:7]
	v_cmpx_lt_i32_e32 vcc, 1, v12
	global_load_dword v97, v13, s[6:7] offset:8
	v_cmpx_lt_i32_e32 vcc, 2, v12
	global_load_dword v98, v13, s[6:7] offset:16
	v_cmpx_lt_i32_e32 vcc, 3, v12
	global_load_dword v99, v13, s[6:7] offset:24
	v_cmpx_lt_i32_e32 vcc, 4, v12
	global_load_dword v100, v13, s[6:7] offset:32
	v_cmpx_lt_i32_e32 vcc, 5, v12
	global_load_dword v101, v13, s[6:7] offset:40
	v_cmpx_lt_i32_e32 vcc, 6, v12
	global_load_dword v102, v13, s[6:7] offset:48
	v_cmpx_lt_i32_e32 vcc, 7, v12
	global_load_dword v103, v13, s[6:7] offset:56
	v_cmpx_lt_i32_e32 vcc, 8, v12
	global_load_dword v104, v13, s[6:7] offset:64
	v_cmpx_lt_i32_e32 vcc, 9, v12
	global_load_dword v105, v13, s[6:7] offset:72
	v_cmpx_lt_i32_e32 vcc, 10, v12
	global_load_dword v106, v13, s[6:7] offset:80
	v_cmpx_lt_i32_e32 vcc, 11, v12
	global_load_dword v107, v13, s[6:7] offset:88
	v_cmpx_lt_i32_e32 vcc, 12, v12
	global_load_dword v108, v13, s[6:7] offset:96
	v_cmpx_lt_i32_e32 vcc, 13, v12
	global_load_dword v109, v13, s[6:7] offset:104
	v_cmpx_lt_i32_e32 vcc, 14, v12
	global_load_dword v110, v13, s[6:7] offset:112
	v_cmpx_lt_i32_e32 vcc, 15, v12
	global_load_dword v111, v13, s[6:7] offset:120
	v_cmpx_lt_i32_e32 vcc, 16, v12
	global_load_dword v112, v13, s[6:7] offset:128
	v_cmpx_lt_i32_e32 vcc, 17, v12
	global_load_dword v113, v13, s[6:7] offset:136
	v_cmpx_lt_i32_e32 vcc, 18, v12
	global_load_dword v114, v13, s[6:7] offset:144
	v_cmpx_lt_i32_e32 vcc, 19, v12
	global_load_dword v115, v13, s[6:7] offset:152
	v_cmpx_lt_i32_e32 vcc, 20, v12
	global_load_dword v116, v13, s[6:7] offset:160
	v_cmpx_lt_i32_e32 vcc, 21, v12
	global_load_dword v117, v13, s[6:7] offset:168
	v_cmpx_lt_i32_e32 vcc, 22, v12
	global_load_dword v118, v13, s[6:7] offset:176
	v_cmpx_lt_i32_e32 vcc, 23, v12
	global_load_dword v119, v13, s[6:7] offset:184
	v_cmpx_lt_i32_e32 vcc, 24, v12
	global_load_dword v120, v13, s[6:7] offset:192
	v_cmpx_lt_i32_e32 vcc, 25, v12
	global_load_dword v121, v13, s[6:7] offset:200
	v_cmpx_lt_i32_e32 vcc, 26, v12
	global_load_dword v122, v13, s[6:7] offset:208
	v_cmpx_lt_i32_e32 vcc, 27, v12
	global_load_dword v123, v13, s[6:7] offset:216
	v_cmpx_lt_i32_e32 vcc, 28, v12
	global_load_dword v124, v13, s[6:7] offset:224
	v_cmpx_lt_i32_e32 vcc, 29, v12
	global_load_dword v125, v13, s[6:7] offset:232
	v_cmpx_lt_i32_e32 vcc, 30, v12
	global_load_dword v126, v13, s[6:7] offset:240
	v_cmpx_lt_i32_e32 vcc, 31, v12
	global_load_dword v127, v13, s[6:7] offset:248
	s_waitcnt vmcnt(0)
	s_mov_b64 exec, s[20:21]
	s_cmp_eq_u32 s74, 2
	s_cbranch_scc1 .Lcvt2_one_minus
	v_cmpx_lt_i32_e32 vcc, 0, v12
	v_mul_f32_e32 v64, v64, v96
	v_cmpx_lt_i32_e32 vcc, 1, v12
	v_mul_f32_e32 v65, v65, v97
	v_cmpx_lt_i32_e32 vcc, 2, v12
	v_mul_f32_e32 v66, v66, v98
	v_cmpx_lt_i32_e32 vcc, 3, v12
	v_mul_f32_e32 v67, v67, v99
	v_cmpx_lt_i32_e32 vcc, 4, v12
	v_mul_f32_e32 v68, v68, v100
	v_cmpx_lt_i32_e32 vcc, 5, v12
	v_mul_f32_e32 v69, v69, v101
	v_cmpx_lt_i32_e32 vcc, 6, v12
	v_mul_f32_e32 v70, v70, v102
	v_cmpx_lt_i32_e32 vcc, 7, v12
	v_mul_f32_e32 v71, v71, v103
	v_cmpx_lt_i32_e32 vcc, 8, v12
	v_mul_f32_e32 v72, v72, v104
	v_cmpx_lt_i32_e32 vcc, 9, v12
	v_mul_f32_e32 v73, v73, v105
	v_cmpx_lt_i32_e32 vcc, 10, v12
	v_mul_f32_e32 v74, v74, v106
	v_cmpx_lt_i32_e32 vcc, 11, v12
	v_mul_f32_e32 v75, v75, v107
	v_cmpx_lt_i32_e32 vcc, 12, v12
	v_mul_f32_e32 v76, v76, v108
	v_cmpx_lt_i32_e32 vcc, 13, v12
	v_mul_f32_e32 v77, v77, v109
	v_cmpx_lt_i32_e32 vcc, 14, v12
	v_mul_f32_e32 v78, v78, v110
	v_cmpx_lt_i32_e32 vcc, 15, v12
	v_mul_f32_e32 v79, v79, v111
	v_cmpx_lt_i32_e32 vcc, 16, v12
	v_mul_f32_e32 v80, v80, v112
	v_cmpx_lt_i32_e32 vcc, 17, v12
	v_mul_f32_e32 v81, v81, v113
	v_cmpx_lt_i32_e32 vcc, 18, v12
	v_mul_f32_e32 v82, v82, v114
	v_cmpx_lt_i32_e32 vcc, 19, v12
	v_mul_f32_e32 v83, v83, v115
	v_cmpx_lt_i32_e32 vcc, 20, v12
	v_mul_f32_e32 v84, v84, v116
	v_cmpx_lt_i32_e32 vcc, 21, v12
	v_mul_f32_e32 v85, v85, v117
	v_cmpx_lt_i32_e32 vcc, 22, v12
	v_mul_f32_e32 v86, v86, v118
	v_cmpx_lt_i32_e32 vcc, 23, v12
	v_mul_f32_e32 v87, v87, v119
	v_cmpx_lt_i32_e32 vcc, 24, v12
	v_mul_f32_e32 v88, v88, v120
	v_cmpx_lt_i32_e32 vcc, 25, v12
	v_mul_f32_e32 v89, v89, v121
	v_cmpx_lt_i32_e32 vcc, 26, v12
	v_mul_f32_e32 v90, v90, v122
	v_cmpx_lt_i32_e32 vcc, 27, v12
	v_mul_f32_e32 v91, v91, v123
	v_cmpx_lt_i32_e32 vcc, 28, v12
	v_mul_f32_e32 v92, v92, v124
	v_cmpx_lt_i32_e32 vcc, 29, v12
	v_mul_f32_e32 v93, v93, v125
	v_cmpx_lt_i32_e32 vcc, 30, v12
	v_mul_f32_e32 v94, v94, v126
	v_cmpx_lt_i32_e32 vcc, 31, v12
	v_mul_f32_e32 v95, v95, v127
	s_branch .Lcvt2_plain

; DI void cvt_item(const CvtJob& J, int item, LAS float* scr, int lane) {
;     ...
;         scr[kk * 33 + (lane & 31)] = v; }
.Lcvt2_plain:
	s_waitcnt vmcnt(0)
	s_mov_b64 exec, s[20:21]
	ds_write_b32 v15, v64
	ds_write_b32 v15, v65 offset:264
	ds_write_b32 v15, v66 offset:528
	ds_write_b32 v15, v67 offset:792
	ds_write_b32 v15, v68 offset:1056
	ds_write_b32 v15, v69 offset:1320
	ds_write_b32 v15, v70 offset:1584
	ds_write_b32 v15, v71 offset:1848
	ds_write_b32 v15, v72 offset:2112
	ds_write_b32 v15, v73 offset:2376
	ds_write_b32 v15, v74 offset:2640
	ds_write_b32 v15, v75 offset:2904
	ds_write_b32 v15, v76 offset:3168
	ds_write_b32 v15, v77 offset:3432
	ds_write_b32 v15, v78 offset:3696
	ds_write_b32 v15, v79 offset:3960
	ds_write_b32 v15, v80 offset:4224
	ds_write_b32 v15, v81 offset:4488
	ds_write_b32 v15, v82 offset:4752
	ds_write_b32 v15, v83 offset:5016
	ds_write_b32 v15, v84 offset:5280
	ds_write_b32 v15, v85 offset:5544
	ds_write_b32 v15, v86 offset:5808
	ds_write_b32 v15, v87 offset:6072
	ds_write_b32 v15, v88 offset:6336
	ds_write_b32 v15, v89 offset:6600
	ds_write_b32 v15, v90 offset:6864
	ds_write_b32 v15, v91 offset:7128
	ds_write_b32 v15, v92 offset:7392
	ds_write_b32 v15, v93 offset:7656
	ds_write_b32 v15, v94 offset:7920
	ds_write_b32 v15, v95 offset:8184
	v_add_u32_e32 v15, 0x2100, v15
	s_movk_i32 s24, 64

; #define LAS __attribute__((address_space(3)))
; DI void cvt_item(const CvtJob& J, int item, LAS float* scr, int lane) {
;     const int nblk = (J.N + 31) >> 5, kb = item / nblk, nb = item % nblk, k0 = 64 * kb, n0 = 32 * nb;
; #pragma unroll 8
;     for (int i = 0; i < 32; ++i) { const int kk = 2 * i + (lane >> 5), k = k0 + kk, n = n0 + (lane & 31);
;         float v = 0.f; if (k < J.K && n < J.N) { v = J.src[(size_t)k * J.ldw + n]; if (J.smode == 1) v *= J.scale[k]; else if (J.smode == 2) v *= (1.f - J.scale[k]); }
;         scr[kk * 33 + (lane & 31)] = v; }
.LBB0_2535:
	v_ashrrev_i32_e32 v4, 31, v24
	s_waitcnt vmcnt(0)
	v_xor_b32_e32 v12, s72, v4
	v_sub_u32_e32 v4, 0, v24
	v_max_i32_e32 v4, v24, v4
	v_mul_hi_u32 v6, v4, v25
	v_mul_lo_u32 v7, v6, s69
	v_sub_u32_e32 v4, v4, v7
	v_add_u32_e32 v7, 1, v6
	v_cmp_le_u32_e32 vcc, s69, v4
	s_mov_b32 s22, 0
	v_mov_b32_e32 v15, v21
	v_cndmask_b32_e32 v6, v6, v7, vcc
	v_subrev_u32_e32 v7, s69, v4
	v_cndmask_b32_e32 v4, v4, v7, vcc
	v_add_u32_e32 v7, 1, v6
	v_cmp_le_u32_e32 vcc, s69, v4
	s_nop 1
	v_cndmask_b32_e32 v4, v6, v7, vcc
	v_xor_b32_e32 v13, v4, v12
	v_sub_u32_e32 v6, v13, v12
	v_mul_lo_u32 v4, v6, s68
	v_sub_u32_e32 v4, v24, v4
	v_lshlrev_b32_e32 v26, 5, v4
	v_lshlrev_b32_e32 v6, 6, v6
	v_or_b32_e32 v10, v26, v3
	v_ashrrev_i32_e32 v11, 31, v10
	v_ashrrev_i32_e32 v7, 31, v6
	v_lshl_add_u64 v[8:9], v[10:11], 2, s[4:5]
	v_cmp_gt_i32_e64 s[2:3], s11, v10
	v_or_b32_e32 v10, v0, v6
	v_mov_b32_e32 v11, v7
	v_lshl_or_b32 v13, v13, 6, v0
	v_lshlrev_b32_e32 v12, 6, v12
	v_sub_u32_e32 v14, v13, v12
	v_lshl_add_u64 v[10:11], v[10:11], 2, s[14:15]
	s_mov_b64 s[18:19], exec
	v_sub_u32_e32 v12, s10, v14
	v_add_u32_e32 v12, 1, v12
	v_ashrrev_i32_e32 v12, 1, v12
	v_med3_i32 v12, v12, 0, 32
	v_cndmask_b32_e64 v12, 0, v12, s[2:3]
	v_mad_i64_i32 v[28:29], s[20:21], v14, s70, 0
	v_lshl_add_u64 v[28:29], v[28:29], 2, v[8:9]
	s_lshl_b32 s20, s70, 3
	s_mov_b32 s21, 0
	v_mov_b32_e32 v64, 0
	v_mov_b32_e32 v65, 0
	v_mov_b32_e32 v66, 0
	v_mov_b32_e32 v67, 0
	v_mov_b32_e32 v68, 0
	v_mov_b32_e32 v69, 0
	v_mov_b32_e32 v70, 0
	v_mov_b32_e32 v71, 0
	v_mov_b32_e32 v72, 0
	v_mov_b32_e32 v73, 0
	v_mov_b32_e32 v74, 0
	v_mov_b32_e32 v75, 0
	v_mov_b32_e32 v76, 0
	v_mov_b32_e32 v77, 0
	v_mov_b32_e32 v78, 0
	v_mov_b32_e32 v79, 0
	v_mov_b32_e32 v80, 0
	v_mov_b32_e32 v81, 0
	v_mov_b32_e32 v82, 0
	v_mov_b32_e32 v83, 0
	v_mov_b32_e32 v84, 0
	v_mov_b32_e32 v85, 0
	v_mov_b32_e32 v86, 0
	v_mov_b32_e32 v87, 0
	v_mov_b32_e32 v88, 0
	v_mov_b32_e32 v89, 0
	v_mov_b32_e32 v90, 0
	v_mov_b32_e32 v91, 0
	v_mov_b32_e32 v92, 0
	v_mov_b32_e32 v93, 0
	v_mov_b32_e32 v94, 0
	v_mov_b32_e32 v95, 0
	v_cmpx_lt_i32_e32 vcc, 0, v12
	global_load_dword v64, v[28:29], off
	v_lshl_add_u64 v[28:29], v[28:29], 0, s[20:21]
	v_cmpx_lt_i32_e32 vcc, 1, v12
	global_load_dword v65, v[28:29], off
	v_lshl_add_u64 v[28:29], v[28:29], 0, s[20:21]
	v_cmpx_lt_i32_e32 vcc, 2, v12
	global_load_dword v66, v[28:29], off
	v_lshl_add_u64 v[28:29], v[28:29], 0, s[20:21]
	v_cmpx_lt_i32_e32 vcc, 3, v12
	global_load_dword v67, v[28:29], off
	v_lshl_add_u64 v[28:29], v[28:29], 0, s[20:21]
	v_cmpx_lt_i32_e32 vcc, 4, v12
	global_load_dword v68, v[28:29], off
	v_lshl_add_u64 v[28:29], v[28:29], 0, s[20:21]
	v_cmpx_lt_i32_e32 vcc, 5, v12
	global_load_dword v69, v[28:29], off
	v_lshl_add_u64 v[28:29], v[28:29], 0, s[20:21]
	v_cmpx_lt_i32_e32 vcc, 6, v12
	global_load_dword v70, v[28:29], off
	v_lshl_add_u64 v[28:29], v[28:29], 0, s[20:21]
	v_cmpx_lt_i32_e32 vcc, 7, v12
	global_load_dword v71, v[28:29], off
	v_lshl_add_u64 v[28:29], v[28:29], 0, s[20:21]
	v_cmpx_lt_i32_e32 vcc, 8, v12
	global_load_dword v72, v[28:29], off
	v_lshl_add_u64 v[28:29], v[28:29], 0, s[20:21]
	v_cmpx_lt_i32_e32 vcc, 9, v12
	global_load_dword v73, v[28:29], off
	v_lshl_add_u64 v[28:29], v[28:29], 0, s[20:21]
	v_cmpx_lt_i32_e32 vcc, 10, v12
	global_load_dword v74, v[28:29], off
	v_lshl_add_u64 v[28:29], v[28:29], 0, s[20:21]
	v_cmpx_lt_i32_e32 vcc, 11, v12
	global_load_dword v75, v[28:29], off
	v_lshl_add_u64 v[28:29], v[28:29], 0, s[20:21]
	v_cmpx_lt_i32_e32 vcc, 12, v12
	global_load_dword v76, v[28:29], off
	v_lshl_add_u64 v[28:29], v[28:29], 0, s[20:21]
	v_cmpx_lt_i32_e32 vcc, 13, v12
	global_load_dword v77, v[28:29], off
	v_lshl_add_u64 v[28:29], v[28:29], 0, s[20:21]
	v_cmpx_lt_i32_e32 vcc, 14, v12
	global_load_dword v78, v[28:29], off
	v_lshl_add_u64 v[28:29], v[28:29], 0, s[20:21]
	v_cmpx_lt_i32_e32 vcc, 15, v12
	global_load_dword v79, v[28:29], off
	v_lshl_add_u64 v[28:29], v[28:29], 0, s[20:21]
	v_cmpx_lt_i32_e32 vcc, 16, v12
	global_load_dword v80, v[28:29], off
	v_lshl_add_u64 v[28:29], v[28:29], 0, s[20:21]
	v_cmpx_lt_i32_e32 vcc, 17, v12
	global_load_dword v81, v[28:29], off
	v_lshl_add_u64 v[28:29], v[28:29], 0, s[20:21]
	v_cmpx_lt_i32_e32 vcc, 18, v12
	global_load_dword v82, v[28:29], off
	v_lshl_add_u64 v[28:29], v[28:29], 0, s[20:21]
	v_cmpx_lt_i32_e32 vcc, 19, v12
	global_load_dword v83, v[28:29], off
	v_lshl_add_u64 v[28:29], v[28:29], 0, s[20:21]
	v_cmpx_lt_i32_e32 vcc, 20, v12
	global_load_dword v84, v[28:29], off
	v_lshl_add_u64 v[28:29], v[28:29], 0, s[20:21]
	v_cmpx_lt_i32_e32 vcc, 21, v12
	global_load_dword v85, v[28:29], off
	v_lshl_add_u64 v[28:29], v[28:29], 0, s[20:21]
	v_cmpx_lt_i32_e32 vcc, 22, v12
	global_load_dword v86, v[28:29], off
	v_lshl_add_u64 v[28:29], v[28:29], 0, s[20:21]
	v_cmpx_lt_i32_e32 vcc, 23, v12
	global_load_dword v87, v[28:29], off
	v_lshl_add_u64 v[28:29], v[28:29], 0, s[20:21]
	v_cmpx_lt_i32_e32 vcc, 24, v12
	global_load_dword v88, v[28:29], off
	v_lshl_add_u64 v[28:29], v[28:29], 0, s[20:21]
	v_cmpx_lt_i32_e32 vcc, 25, v12
	global_load_dword v89, v[28:29], off
	v_lshl_add_u64 v[28:29], v[28:29], 0, s[20:21]
	v_cmpx_lt_i32_e32 vcc, 26, v12
	global_load_dword v90, v[28:29], off
	v_lshl_add_u64 v[28:29], v[28:29], 0, s[20:21]
	v_cmpx_lt_i32_e32 vcc, 27, v12
	global_load_dword v91, v[28:29], off
	v_lshl_add_u64 v[28:29], v[28:29], 0, s[20:21]
	v_cmpx_lt_i32_e32 vcc, 28, v12
	global_load_dword v92, v[28:29], off
	v_lshl_add_u64 v[28:29], v[28:29], 0, s[20:21]
	v_cmpx_lt_i32_e32 vcc, 29, v12
	global_load_dword v93, v[28:29], off
	v_lshl_add_u64 v[28:29], v[28:29], 0, s[20:21]
	v_cmpx_lt_i32_e32 vcc, 30, v12
	global_load_dword v94, v[28:29], off
	v_lshl_add_u64 v[28:29], v[28:29], 0, s[20:21]
	v_cmpx_lt_i32_e32 vcc, 31, v12
	global_load_dword v95, v[28:29], off
	s_mov_b64 exec, s[18:19]
	s_cmp_eq_u32 s71, 0
	s_cbranch_scc1 .Lcvt3_plain
; DI void cvt_item(const CvtJob& J, int item, LAS float* scr, int lane) {
;     ...
;         float v = 0.f; if (k < J.K && n < J.N) { v = J.src[(size_t)k * J.ldw + n]; if (J.smode == 1) v *= J.scale[k]; else if (J.smode == 2) v *= (1.f - J.scale[k]); }
	v_lshlrev_b32_e32 v13, 2, v14
	v_cmpx_lt_i32_e32 vcc, 0, v12
	global_load_dword v96, v13, s[6:7]
	v_cmpx_lt_i32_e32 vcc, 1, v12
	global_load_dword v97, v13, s[6:7] offset:8
	v_cmpx_lt_i32_e32 vcc, 2, v12
	global_load_dword v98, v13, s[6:7] offset:16
	v_cmpx_lt_i32_e32 vcc, 3, v12
	global_load_dword v99, v13, s[6:7] offset:24
	v_cmpx_lt_i32_e32 vcc, 4, v12
	global_load_dword v100, v13, s[6:7] offset:32
	v_cmpx_lt_i32_e32 vcc, 5, v12
	global_load_dword v101, v13, s[6:7] offset:40
	v_cmpx_lt_i32_e32 vcc, 6, v12
	global_load_dword v102, v13, s[6:7] offset:48
	v_cmpx_lt_i32_e32 vcc, 7, v12
	global_load_dword v103, v13, s[6:7] offset:56
	v_cmpx_lt_i32_e32 vcc, 8, v12
	global_load_dword v104, v13, s[6:7] offset:64
	v_cmpx_lt_i32_e32 vcc, 9, v12
	global_load_dword v105, v13, s[6:7] offset:72
	v_cmpx_lt_i32_e32 vcc, 10, v12
	global_load_dword v106, v13, s[6:7] offset:80
	v_cmpx_lt_i32_e32 vcc, 11, v12
	global_load_dword v107, v13, s[6:7] offset:88
	v_cmpx_lt_i32_e32 vcc, 12, v12
	global_load_dword v108, v13, s[6:7] offset:96
	v_cmpx_lt_i32_e32 vcc, 13, v12
	global_load_dword v109, v13, s[6:7] offset:104
	v_cmpx_lt_i32_e32 vcc, 14, v12
	global_load_dword v110, v13, s[6:7] offset:112
	v_cmpx_lt_i32_e32 vcc, 15, v12
	global_load_dword v111, v13, s[6:7] offset:120
	v_cmpx_lt_i32_e32 vcc, 16, v12
	global_load_dword v112, v13, s[6:7] offset:128
	v_cmpx_lt_i32_e32 vcc, 17, v12
	global_load_dword v113, v13, s[6:7] offset:136
	v_cmpx_lt_i32_e32 vcc, 18, v12
	global_load_dword v114, v13, s[6:7] offset:144
	v_cmpx_lt_i32_e32 vcc, 19, v12
	global_load_dword v115, v13, s[6:7] offset:152
	v_cmpx_lt_i32_e32 vcc, 20, v12
	global_load_dword v116, v13, s[6:7] offset:160
	v_cmpx_lt_i32_e32 vcc, 21, v12
	global_load_dword v117, v13, s[6:7] offset:168
	v_cmpx_lt_i32_e32 vcc, 22, v12
	global_load_dword v118, v13, s[6:7] offset:176
	v_cmpx_lt_i32_e32 vcc, 23, v12
	global_load_dword v119, v13, s[6:7] offset:184
	v_cmpx_lt_i32_e32 vcc, 24, v12
	global_load_dword v120, v13, s[6:7] offset:192
	v_cmpx_lt_i32_e32 vcc, 25, v12
	global_load_dword v121, v13, s[6:7] offset:200
	v_cmpx_lt_i32_e32 vcc, 26, v12
	global_load_dword v122, v13, s[6:7] offset:208
	v_cmpx_lt_i32_e32 vcc, 27, v12
	global_load_dword v123, v13, s[6:7] offset:216
	v_cmpx_lt_i32_e32 vcc, 28, v12
	global_load_dword v124, v13, s[6:7] offset:224
	v_cmpx_lt_i32_e32 vcc, 29, v12
	global_load_dword v125, v13, s[6:7] offset:232
	v_cmpx_lt_i32_e32 vcc, 30, v12
	global_load_dword v126, v13, s[6:7] offset:240
	v_cmpx_lt_i32_e32 vcc, 31, v12
	global_load_dword v127, v13, s[6:7] offset:248
	s_waitcnt vmcnt(0)
	s_mov_b64 exec, s[18:19]
	s_cmp_eq_u32 s71, 2
	s_cbranch_scc1 .Lcvt3_one_minus
	v_cmpx_lt_i32_e32 vcc, 0, v12
	v_mul_f32_e32 v64, v64, v96
	v_cmpx_lt_i32_e32 vcc, 1, v12
	v_mul_f32_e32 v65, v65, v97
	v_cmpx_lt_i32_e32 vcc, 2, v12
	v_mul_f32_e32 v66, v66, v98
	v_cmpx_lt_i32_e32 vcc, 3, v12
	v_mul_f32_e32 v67, v67, v99
	v_cmpx_lt_i32_e32 vcc, 4, v12
	v_mul_f32_e32 v68, v68, v100
	v_cmpx_lt_i32_e32 vcc, 5, v12
	v_mul_f32_e32 v69, v69, v101
	v_cmpx_lt_i32_e32 vcc, 6, v12
	v_mul_f32_e32 v70, v70, v102
	v_cmpx_lt_i32_e32 vcc, 7, v12
	v_mul_f32_e32 v71, v71, v103
	v_cmpx_lt_i32_e32 vcc, 8, v12
	v_mul_f32_e32 v72, v72, v104
	v_cmpx_lt_i32_e32 vcc, 9, v12
	v_mul_f32_e32 v73, v73, v105
	v_cmpx_lt_i32_e32 vcc, 10, v12
	v_mul_f32_e32 v74, v74, v106
	v_cmpx_lt_i32_e32 vcc, 11, v12
	v_mul_f32_e32 v75, v75, v107
	v_cmpx_lt_i32_e32 vcc, 12, v12
	v_mul_f32_e32 v76, v76, v108
	v_cmpx_lt_i32_e32 vcc, 13, v12
	v_mul_f32_e32 v77, v77, v109
	v_cmpx_lt_i32_e32 vcc, 14, v12
	v_mul_f32_e32 v78, v78, v110
	v_cmpx_lt_i32_e32 vcc, 15, v12
	v_mul_f32_e32 v79, v79, v111
	v_cmpx_lt_i32_e32 vcc, 16, v12
	v_mul_f32_e32 v80, v80, v112
	v_cmpx_lt_i32_e32 vcc, 17, v12
	v_mul_f32_e32 v81, v81, v113
	v_cmpx_lt_i32_e32 vcc, 18, v12
	v_mul_f32_e32 v82, v82, v114
	v_cmpx_lt_i32_e32 vcc, 19, v12
	v_mul_f32_e32 v83, v83, v115
	v_cmpx_lt_i32_e32 vcc, 20, v12
	v_mul_f32_e32 v84, v84, v116
	v_cmpx_lt_i32_e32 vcc, 21, v12
	v_mul_f32_e32 v85, v85, v117
	v_cmpx_lt_i32_e32 vcc, 22, v12
	v_mul_f32_e32 v86, v86, v118
	v_cmpx_lt_i32_e32 vcc, 23, v12
	v_mul_f32_e32 v87, v87, v119
	v_cmpx_lt_i32_e32 vcc, 24, v12
	v_mul_f32_e32 v88, v88, v120
	v_cmpx_lt_i32_e32 vcc, 25, v12
	v_mul_f32_e32 v89, v89, v121
	v_cmpx_lt_i32_e32 vcc, 26, v12
	v_mul_f32_e32 v90, v90, v122
	v_cmpx_lt_i32_e32 vcc, 27, v12
	v_mul_f32_e32 v91, v91, v123
	v_cmpx_lt_i32_e32 vcc, 28, v12
	v_mul_f32_e32 v92, v92, v124
	v_cmpx_lt_i32_e32 vcc, 29, v12
	v_mul_f32_e32 v93, v93, v125
	v_cmpx_lt_i32_e32 vcc, 30, v12
	v_mul_f32_e32 v94, v94, v126
	v_cmpx_lt_i32_e32 vcc, 31, v12
	v_mul_f32_e32 v95, v95, v127
	s_branch .Lcvt3_plain
